# job0 (prompt FoX) QK: eight K fragments per 64-key step read up front into own registers, per-group MFMA blocks straight-line with counted waits
# speedup vs baseline: 1.0045x; 1.0045x over previous
.LBB0_1039:
	s_cmp_lt_u32 s65, s55
	s_cselect_b64 s[10:11], -1, 0
	s_cmp_le_i32 s65, s63
	s_cselect_b64 s[12:13], -1, 0
	s_and_b64 s[10:11], s[10:11], s[12:13]
	s_cmp_lt_u32 s65, s56
	s_cselect_b64 s[12:13], -1, 0
	s_cmp_le_i32 s65, s64
	s_cselect_b64 s[38:39], -1, 0
	s_and_b64 s[60:61], s[12:13], s[38:39]
	s_or_b64 s[12:13], s[10:11], s[60:61]
	s_andn2_b64 vcc, exec, s[12:13]
	s_cbranch_vccnz .LBB0_1055
	v_add_u32_e32 v98, 0, v198
	ds_read_b128 v[66:69], v98 offset:18432
	ds_read_b128 v[70:73], v98 offset:18464
	ds_read_b128 v[74:77], v98 offset:18496
	ds_read_b128 v[78:81], v98 offset:18528
	ds_read_b128 v[82:85], v98 offset:18560
	ds_read_b128 v[86:89], v98 offset:18592
	ds_read_b128 v[90:93], v98 offset:18624
	ds_read_b128 v[94:97], v98 offset:18656
	v_add_u32_e32 v206, v196, v198
	ds_read_b128 v[182:185], v206
	ds_read_b128 v[178:181], v206 offset:4608
	ds_read_b128 v[220:223], v206 offset:32
	ds_read_b128 v[224:227], v206 offset:4640
	ds_read_b128 v[228:231], v206 offset:64
	ds_read_b128 v[232:235], v206 offset:4672
	ds_read_b128 v[236:239], v206 offset:96
	ds_read_b128 v[240:243], v206 offset:4704
	v_cndmask_b32_e64 v98, 0, 1, s[10:11]
	v_cmp_ne_u32_e64 s[12:13], 1, v98
	v_cndmask_b32_e64 v207, 0, 1, s[60:61]
	v_cmp_ne_u32_e64 s[10:11], 1, v207
	s_and_b64 vcc, exec, s[12:13]
	s_cbranch_vccnz .Lj0q1_a0
	s_waitcnt lgkmcnt(7)
	v_mfma_f32_32x32x16_bf16 v[114:129], v[182:185], v[130:133], v[66:81]
	s_waitcnt lgkmcnt(6)
	v_mfma_f32_32x32x16_bf16 v[98:113], v[178:181], v[130:133], v[82:97]
.Lj0q1_a0:
	s_and_b64 vcc, exec, s[10:11]
	s_cbranch_vccnz .Lj0q1_b0
	s_waitcnt lgkmcnt(7)
	s_nop 0
	v_mfma_f32_32x32x16_bf16 v[66:81], v[182:185], v[146:149], v[66:81]
	s_waitcnt lgkmcnt(6)
	v_mfma_f32_32x32x16_bf16 v[82:97], v[178:181], v[146:149], v[82:97]
.Lj0q1_b0:
	s_and_b64 vcc, exec, s[12:13]
	s_cbranch_vccnz .Lj0q1_a1
	s_waitcnt lgkmcnt(5)
	v_mfma_f32_32x32x16_bf16 v[114:129], v[220:223], v[134:137], v[114:129]
	s_waitcnt lgkmcnt(4)
	v_mfma_f32_32x32x16_bf16 v[98:113], v[224:227], v[134:137], v[98:113]
.Lj0q1_a1:
	s_and_b64 vcc, exec, s[10:11]
	s_cbranch_vccnz .Lj0q1_b1
	s_waitcnt lgkmcnt(5)
	s_nop 0
	v_mfma_f32_32x32x16_bf16 v[66:81], v[220:223], v[150:153], v[66:81]
	s_waitcnt lgkmcnt(4)
	v_mfma_f32_32x32x16_bf16 v[82:97], v[224:227], v[150:153], v[82:97]
.Lj0q1_b1:
	s_and_b64 vcc, exec, s[12:13]
	s_cbranch_vccnz .Lj0q1_a2
	s_waitcnt lgkmcnt(3)
	v_mfma_f32_32x32x16_bf16 v[114:129], v[228:231], v[138:141], v[114:129]
	s_waitcnt lgkmcnt(2)
	v_mfma_f32_32x32x16_bf16 v[98:113], v[232:235], v[138:141], v[98:113]
.Lj0q1_a2:
	s_and_b64 vcc, exec, s[10:11]
	s_cbranch_vccnz .Lj0q1_b2
	s_waitcnt lgkmcnt(3)
	s_nop 0
	v_mfma_f32_32x32x16_bf16 v[66:81], v[228:231], v[154:157], v[66:81]
	s_waitcnt lgkmcnt(2)
	v_mfma_f32_32x32x16_bf16 v[82:97], v[232:235], v[154:157], v[82:97]
.Lj0q1_b2:
	s_and_b64 vcc, exec, s[12:13]
	s_cbranch_vccnz .Lj0q1_a3
	s_waitcnt lgkmcnt(1)
	v_mfma_f32_32x32x16_bf16 v[114:129], v[236:239], v[142:145], v[114:129]
	s_waitcnt lgkmcnt(0)
	v_mfma_f32_32x32x16_bf16 v[98:113], v[240:243], v[142:145], v[98:113]
.Lj0q1_a3:
	s_and_b64 vcc, exec, s[10:11]
	s_cbranch_vccnz .Lj0q1_b3
	s_waitcnt lgkmcnt(1)
	s_nop 0
	v_mfma_f32_32x32x16_bf16 v[66:81], v[236:239], v[158:161], v[66:81]
	s_waitcnt lgkmcnt(0)
	v_mfma_f32_32x32x16_bf16 v[82:97], v[240:243], v[158:161], v[82:97]
.Lj0q1_b3:
.LBB0_1048:
	s_and_b64 vcc, exec, s[12:13]
	s_add_i32 s38, s65, 63
	s_cbranch_vccnz .LBB0_1064

.LBB0_1055:
	v_mov_b32_e32 v207, v205
	v_mov_b32_e32 v206, v204
	s_branch .LBB0_1086
.LBB0_1064:
	v_mov_b32_e32 v207, v205
	s_and_b64 vcc, exec, s[10:11]
	s_cbranch_vccnz .LBB0_1054

.LBB0_1095:
	s_add_i32 s38, s65, 64
	s_cmp_lt_u32 s38, s55
	s_cselect_b64 s[10:11], -1, 0
	s_cmp_le_i32 s38, s63
	s_cselect_b64 s[12:13], -1, 0
	s_and_b64 s[10:11], s[10:11], s[12:13]
	s_cmp_lt_u32 s38, s56
	s_cselect_b64 s[12:13], -1, 0
	s_cmp_le_i32 s38, s64
	s_cselect_b64 s[38:39], -1, 0
	s_and_b64 s[60:61], s[12:13], s[38:39]
	s_or_b64 s[12:13], s[10:11], s[60:61]
	s_andn2_b64 vcc, exec, s[12:13]
	s_cbranch_vccnz .LBB0_1112
	v_add_u32_e32 v98, 0, v198
	ds_read_b128 v[66:69], v98 offset:51200
	ds_read_b128 v[70:73], v98 offset:51232
	ds_read_b128 v[74:77], v98 offset:51264
	ds_read_b128 v[78:81], v98 offset:51296
	ds_read_b128 v[82:85], v98 offset:51328
	ds_read_b128 v[86:89], v98 offset:51360
	ds_read_b128 v[90:93], v98 offset:51392
	ds_read_b128 v[94:97], v98 offset:51424
	v_add_u32_e32 v204, v196, v198
	ds_read_b128 v[182:185], v204 offset:32768
	ds_read_b128 v[178:181], v204 offset:37376
	ds_read_b128 v[220:223], v204 offset:32800
	ds_read_b128 v[224:227], v204 offset:37408
	ds_read_b128 v[228:231], v204 offset:32832
	ds_read_b128 v[232:235], v204 offset:37440
	ds_read_b128 v[236:239], v204 offset:32864
	ds_read_b128 v[240:243], v204 offset:37472
	v_cndmask_b32_e64 v98, 0, 1, s[10:11]
	v_cmp_ne_u32_e64 s[12:13], 1, v98
	v_cndmask_b32_e64 v205, 0, 1, s[60:61]
	v_cmp_ne_u32_e64 s[10:11], 1, v205
	s_and_b64 vcc, exec, s[12:13]
	s_cbranch_vccnz .Lj0q2_a0
	s_waitcnt lgkmcnt(7)
	v_mfma_f32_32x32x16_bf16 v[114:129], v[182:185], v[130:133], v[66:81]
	s_waitcnt lgkmcnt(6)
	v_mfma_f32_32x32x16_bf16 v[98:113], v[178:181], v[130:133], v[82:97]

.Lj0q2_b3:
.LBB0_1104:
	s_and_b64 vcc, exec, s[12:13]
	s_add_i32 s38, s65, 0x7f
	s_cbranch_vccnz .LBB0_1121

.LBB0_1112:
	v_mov_b32_e32 v205, v207
	v_mov_b32_e32 v204, v206
	s_cmp_ge_u32 s67, s62
	s_cbranch_scc0 .LBB0_1142
	s_branch .LBB0_1145
.LBB0_1121:
	v_mov_b32_e32 v205, v207
	s_and_b64 vcc, exec, s[10:11]
	s_cbranch_vccnz .LBB0_1110
